# cross-tile LDS-DMA prefetch: lean in-proj epilogue issues the next tile's first K-stage into ring buffer 0 (slabs moved to 0x6000); next prologue issues only stage 1
# baseline (speedup 1.0000x reference)
.LBB0_219:
	s_lshr_b32 s2, s4, 2
	s_and_b32 s3, s4, 3
	s_lshl_b32 s3, s3, 3
	s_mov_b32 s6, 0x1001000a
	s_cmp_eq_u32 s2, 1
	s_cselect_b32 s6, 0x171b0611, s6
	s_cmp_eq_u32 s2, 2
	s_cselect_b32 s6, 0xe1c1d08, s6
	s_cmp_eq_u32 s2, 3
	s_cselect_b32 s6, 0x14090203, s6
	s_cmp_eq_u32 s2, 4
	s_cselect_b32 s6, 0x40f0512, s6
	s_cmp_eq_u32 s2, 5
	s_cselect_b32 s6, 0xc160b0d, s6
	s_cmp_eq_u32 s2, 6
	s_cselect_b32 s6, 0x191a1813, s6
	s_cmp_eq_u32 s2, 7
	s_cselect_b32 s6, 0x1507, s6
	s_lshr_b32 s6, s6, s3
	s_and_b32 s4, s6, 0xff
	s_lshl_b32 s5, s5, 8
	s_mov_b32 s32, s5
	v_add_u32_e32 v2, s5, v219
	v_ashrrev_i32_e32 v3, 31, v2
	v_lshlrev_b64 v[4:5], 11, v[2:3]
	v_and_b32_e32 v6, 0xfffe7000, v4
	v_mov_b32_e32 v7, v5
	v_lshlrev_b32_e32 v0, 6, v2
	s_lshl_b32 s6, s4, 7
	v_lshl_add_u64 v[6:7], s[44:45], 0, v[6:7]
	v_and_b32_e32 v0, 64, v0
	v_lshl_add_u64 v[2:3], v[6:7], 0, v[0:1]
	v_add_u32_e32 v6, s6, v220
	v_ashrrev_i32_e32 v7, 31, v6
	v_lshlrev_b64 v[8:9], 11, v[6:7]
	v_and_b32_e32 v10, 0xffff7000, v8
	v_mov_b32_e32 v11, v9
	v_lshlrev_b32_e32 v0, 6, v6
	v_lshl_add_u64 v[10:11], s[42:43], 0, v[10:11]
	v_and_b32_e32 v0, 64, v0
	v_mov_b32_e32 v139, v1
	v_lshl_add_u64 v[6:7], v[10:11], 0, v[0:1]
	v_readfirstlane_b32 s2, v221
	v_add_u32_e32 v0, 0x400, v221
	v_lshl_add_u64 v[2:3], v[2:3], 0, v[138:139]
	s_cmp_eq_u32 s35, 0x5aa51234
	s_cbranch_scc0 .Lmy_pf_novar
	v_lshl_add_u64 v[6:7], v[6:7], 0, v[138:139]
	v_add_u32_e32 v0, 0x6000, v221
	s_mov_b64 s[2:3], 0x80
	v_readfirstlane_b32 s8, v0
	v_lshl_add_u64 v[10:11], v[2:3], 0, s[2:3]
	s_mov_b32 m0, s8
	s_nop 0
	global_load_lds_dwordx4 v[10:11], off
	v_add_u32_e32 v0, 0x6400, v221
	s_mov_b64 s[2:3], 0x8080
	v_readfirstlane_b32 s8, v0
	v_lshl_add_u64 v[10:11], v[2:3], 0, s[2:3]
	s_mov_b32 m0, s8
	s_nop 0
	global_load_lds_dwordx4 v[10:11], off
	v_add_u32_e32 v0, 0x6800, v221
	s_mov_b64 s[2:3], 0x10080
	v_readfirstlane_b32 s8, v0
	v_lshl_add_u64 v[10:11], v[2:3], 0, s[2:3]
	s_mov_b32 m0, s8
	s_nop 0
	global_load_lds_dwordx4 v[10:11], off
	v_add_u32_e32 v0, 0x6c00, v221
	s_mov_b64 s[2:3], 0x18080
	v_readfirstlane_b32 s8, v0
	v_lshl_add_u64 v[10:11], v[2:3], 0, s[2:3]
	s_mov_b32 m0, s8
	s_nop 0
	global_load_lds_dwordx4 v[10:11], off
	v_add_u32_e32 v0, 0xa000, v130
	s_mov_b64 s[2:3], 0x80
	v_readfirstlane_b32 s8, v0
	v_lshl_add_u64 v[10:11], v[6:7], 0, s[2:3]
	s_mov_b32 m0, s8
	s_nop 0
	global_load_lds_dwordx4 v[10:11], off
	v_add_u32_e32 v0, 0xa400, v130
	s_mov_b64 s[2:3], 0x8080
	v_readfirstlane_b32 s8, v0
	v_lshl_add_u64 v[10:11], v[6:7], 0, s[2:3]
	s_mov_b32 m0, s8
	s_nop 0
	global_load_lds_dwordx4 v[10:11], off
	v_and_b32_e32 v8, 0xfffff000, v8
	s_branch .Lmy_pf_join

.LBB0_220:
	s_cmp_gt_i32 s7, 0
	s_waitcnt vmcnt(6)
	s_cselect_b32 s8, -1, 2
	s_mul_i32 s9, s7, 0x6000
	s_waitcnt lgkmcnt(0)
	s_add_i32 s8, s8, s7
	v_add_u32_e32 v139, s9, v224
	v_add_u32_e32 v0, s9, v223
	s_mulk_i32 s8, 0x6000
	v_add_u32_e32 v154, v139, v228
	s_barrier
	v_lshl_add_u64 v[170:171], v[144:145], 0, s[2:3]
	v_add_u32_e32 v141, s8, v221
	v_lshl_add_u64 v[174:175], v[142:143], 0, s[2:3]
	v_add_u32_e32 v182, s8, v222
	v_add_u32_e32 v166, v0, v228
	ds_read_b128 v[146:149], v166
	ds_read_b128 v[150:153], v154
	ds_read_b128 v[154:157], v154 offset:2048
	v_lshl_add_u64 v[172:173], v[170:171], 0, s[88:89]
	v_lshl_add_u64 v[176:177], v[174:175], 0, s[88:89]
	v_add_u32_e32 v183, 0x4000, v182
	v_lshl_add_u64 v[178:179], v[170:171], 0, s[90:91]
	v_add_u32_e32 v184, 0x400, v141
	v_lshl_add_u64 v[180:181], v[170:171], 0, s[78:79]
	v_add_u32_e32 v185, 0x800, v141
	ds_read_b128 v[158:161], v166 offset:2048
	ds_read_b128 v[162:165], v166 offset:4096
	ds_read_b128 v[166:169], v166 offset:6144
	s_waitcnt lgkmcnt(3)
	s_setprio 1
	v_mfma_f32_32x32x16_bf16 v[114:129], v[146:149], v[150:153], v[114:129]
	v_mfma_f32_32x32x16_bf16 v[98:113], v[146:149], v[154:157], v[98:113]
	v_readfirstlane_b32 s8, v141
	s_mov_b32 m0, s8
	s_nop 0
	global_load_lds_dwordx4 v[172:173], off
	s_waitcnt lgkmcnt(2)
	v_mfma_f32_32x32x16_bf16 v[82:97], v[158:161], v[150:153], v[82:97]
	v_mfma_f32_32x32x16_bf16 v[66:81], v[158:161], v[154:157], v[66:81]
	v_readfirstlane_b32 s8, v184
	s_mov_b32 m0, s8
	s_nop 0
	global_load_lds_dwordx4 v[178:179], off
	s_waitcnt lgkmcnt(1)
	v_mfma_f32_32x32x16_bf16 v[50:65], v[162:165], v[150:153], v[50:65]
	v_mfma_f32_32x32x16_bf16 v[34:49], v[162:165], v[154:157], v[34:49]
	v_readfirstlane_b32 s8, v185
	s_mov_b32 m0, s8
	s_nop 0
	global_load_lds_dwordx4 v[180:181], off
	s_waitcnt lgkmcnt(0)
	v_mfma_f32_32x32x16_bf16 v[18:33], v[166:169], v[150:153], v[18:33]
	v_mfma_f32_32x32x16_bf16 v[2:17], v[166:169], v[154:157], v[2:17]
	s_setprio 0
	v_add_u32_e32 v0, v0, v229
	v_add_u32_e32 v139, v139, v229
	ds_read_b128 v[146:149], v0
	ds_read_b128 v[150:153], v139
	ds_read_b128 v[154:157], v139 offset:2048
	ds_read_b128 v[158:161], v0 offset:2048
	ds_read_b128 v[162:165], v0 offset:4096
	ds_read_b128 v[166:169], v0 offset:6144
	s_waitcnt lgkmcnt(3)
	s_setprio 1
	v_mfma_f32_32x32x16_bf16 v[114:129], v[146:149], v[150:153], v[114:129]
	v_mfma_f32_32x32x16_bf16 v[98:113], v[146:149], v[154:157], v[98:113]
	v_add_u32_e32 v0, 0xc00, v141
	v_lshl_add_u64 v[146:147], v[170:171], 0, s[76:77]
	v_readfirstlane_b32 s8, v0
	s_mov_b32 m0, s8
	s_nop 0
	global_load_lds_dwordx4 v[146:147], off
	s_waitcnt lgkmcnt(2)
	v_mfma_f32_32x32x16_bf16 v[82:97], v[158:161], v[150:153], v[82:97]
	v_mfma_f32_32x32x16_bf16 v[66:81], v[158:161], v[154:157], v[66:81]
	v_readfirstlane_b32 s8, v183
	s_mov_b32 m0, s8
	s_nop 0
	global_load_lds_dwordx4 v[176:177], off
	s_waitcnt lgkmcnt(1)
	v_mfma_f32_32x32x16_bf16 v[50:65], v[162:165], v[150:153], v[50:65]
	v_mfma_f32_32x32x16_bf16 v[34:49], v[162:165], v[154:157], v[34:49]
	v_add_u32_e32 v0, 0x4400, v182
	v_lshl_add_u64 v[146:147], v[174:175], 0, s[90:91]
	v_readfirstlane_b32 s8, v0
	s_mov_b32 m0, s8
	s_nop 0
	global_load_lds_dwordx4 v[146:147], off
	s_waitcnt lgkmcnt(0)
	v_mfma_f32_32x32x16_bf16 v[18:33], v[166:169], v[150:153], v[18:33]
	v_mfma_f32_32x32x16_bf16 v[2:17], v[166:169], v[154:157], v[2:17]
	s_setprio 0
	s_add_i32 s8, s7, 1
	s_cmp_lt_i32 s7, 2
	s_cselect_b32 s7, s8, 0
	s_add_u32 s2, s2, 0x80
	s_addc_u32 s3, s3, 0
	s_cmpk_eq_i32 s2, 0xf00
	s_cbranch_scc0 .LBB0_220
	s_waitcnt vmcnt(6)
	s_mul_i32 s2, s7, 0x6000
	s_waitcnt lgkmcnt(0)
	v_add_u32_e32 v139, s2, v224
	v_add_u32_e32 v0, s2, v223
	v_add_u32_e32 v150, v139, v228
	s_barrier
	v_add_u32_e32 v141, v0, v228
	ds_read_b128 v[142:145], v141
	ds_read_b128 v[146:149], v150
	ds_read_b128 v[150:153], v150 offset:2048
	ds_read_b128 v[154:157], v141 offset:2048
	ds_read_b128 v[158:161], v141 offset:4096
	ds_read_b128 v[162:165], v141 offset:6144
	s_waitcnt lgkmcnt(3)
	s_setprio 1
	v_mfma_f32_32x32x16_bf16 v[114:129], v[142:145], v[146:149], v[114:129]
	v_mfma_f32_32x32x16_bf16 v[98:113], v[142:145], v[150:153], v[98:113]
	s_waitcnt lgkmcnt(2)
	v_mfma_f32_32x32x16_bf16 v[82:97], v[154:157], v[146:149], v[82:97]
	v_mfma_f32_32x32x16_bf16 v[66:81], v[154:157], v[150:153], v[66:81]
	s_waitcnt lgkmcnt(1)
	v_mfma_f32_32x32x16_bf16 v[50:65], v[158:161], v[146:149], v[50:65]
	v_mfma_f32_32x32x16_bf16 v[34:49], v[158:161], v[150:153], v[34:49]
	s_waitcnt lgkmcnt(0)
	v_mfma_f32_32x32x16_bf16 v[18:33], v[162:165], v[146:149], v[18:33]
	v_mfma_f32_32x32x16_bf16 v[2:17], v[162:165], v[150:153], v[2:17]
	s_setprio 0
	v_add_u32_e32 v0, v0, v229
	v_add_u32_e32 v139, v139, v229
	ds_read_b128 v[142:145], v0
	ds_read_b128 v[146:149], v139
	ds_read_b128 v[150:153], v139 offset:2048
	ds_read_b128 v[154:157], v0 offset:2048
	ds_read_b128 v[158:161], v0 offset:4096
	ds_read_b128 v[162:165], v0 offset:6144
	s_waitcnt lgkmcnt(3)
	s_setprio 1
	v_mfma_f32_32x32x16_bf16 v[114:129], v[142:145], v[146:149], v[114:129]
	v_mfma_f32_32x32x16_bf16 v[98:113], v[142:145], v[150:153], v[98:113]
	s_waitcnt lgkmcnt(2)
	v_mfma_f32_32x32x16_bf16 v[82:97], v[154:157], v[146:149], v[82:97]
	v_mfma_f32_32x32x16_bf16 v[66:81], v[154:157], v[150:153], v[66:81]
	s_waitcnt lgkmcnt(1)
	v_mfma_f32_32x32x16_bf16 v[50:65], v[158:161], v[146:149], v[50:65]
	v_mfma_f32_32x32x16_bf16 v[34:49], v[158:161], v[150:153], v[34:49]
	s_waitcnt lgkmcnt(0)
	v_mfma_f32_32x32x16_bf16 v[18:33], v[162:165], v[146:149], v[18:33]
	v_mfma_f32_32x32x16_bf16 v[2:17], v[162:165], v[150:153], v[2:17]
	s_setprio 0
	s_waitcnt vmcnt(0)
	s_waitcnt lgkmcnt(0)
	s_barrier
	ds_read_b128 v[142:145], v232
	ds_read_b128 v[146:149], v233
	ds_read_b128 v[150:153], v233 offset:2048
	ds_read_b128 v[154:157], v232 offset:2048
	ds_read_b128 v[158:161], v232 offset:4096
	ds_read_b128 v[162:165], v232 offset:6144
	s_waitcnt lgkmcnt(3)
	s_setprio 1
	v_mfma_f32_32x32x16_bf16 v[114:129], v[142:145], v[146:149], v[114:129]
	v_mfma_f32_32x32x16_bf16 v[98:113], v[142:145], v[150:153], v[98:113]
	s_waitcnt lgkmcnt(2)
	v_mfma_f32_32x32x16_bf16 v[82:97], v[154:157], v[146:149], v[82:97]
	v_mfma_f32_32x32x16_bf16 v[66:81], v[154:157], v[150:153], v[66:81]
	s_waitcnt lgkmcnt(1)
	v_mfma_f32_32x32x16_bf16 v[50:65], v[158:161], v[146:149], v[50:65]
	v_mfma_f32_32x32x16_bf16 v[34:49], v[158:161], v[150:153], v[34:49]
	s_waitcnt lgkmcnt(0)
	v_mfma_f32_32x32x16_bf16 v[18:33], v[162:165], v[146:149], v[18:33]
	v_mfma_f32_32x32x16_bf16 v[2:17], v[162:165], v[150:153], v[2:17]
	s_setprio 0
	ds_read_b128 v[142:145], v234
	ds_read_b128 v[146:149], v235
	ds_read_b128 v[150:153], v235 offset:2048
	ds_read_b128 v[154:157], v234 offset:2048
	ds_read_b128 v[158:161], v234 offset:4096
	ds_read_b128 v[162:165], v234 offset:6144
	s_waitcnt lgkmcnt(3)
	s_setprio 1
	v_mfma_f32_32x32x16_bf16 v[114:129], v[142:145], v[146:149], v[114:129]
	v_mfma_f32_32x32x16_bf16 v[98:113], v[142:145], v[150:153], v[98:113]
	s_waitcnt lgkmcnt(2)
	v_mfma_f32_32x32x16_bf16 v[82:97], v[154:157], v[146:149], v[82:97]
	v_mfma_f32_32x32x16_bf16 v[66:81], v[154:157], v[150:153], v[66:81]
	s_waitcnt lgkmcnt(1)
	v_mfma_f32_32x32x16_bf16 v[50:65], v[158:161], v[146:149], v[50:65]
	v_mfma_f32_32x32x16_bf16 v[34:49], v[158:161], v[150:153], v[34:49]
	s_waitcnt lgkmcnt(0)
	v_mfma_f32_32x32x16_bf16 v[18:33], v[162:165], v[146:149], v[18:33]
	v_mfma_f32_32x32x16_bf16 v[2:17], v[162:165], v[150:153], v[2:17]
	s_setprio 0
	s_cmp_gt_i32 s4, 3
	s_cselect_b64 s[30:31], -1, 0
	s_add_i32 s2, s4, -8
	s_cmp_gt_u32 s2, 5
	s_cselect_b64 s[98:99], -1, 0
	s_and_b32 s2, s4, 0x7ffffffc
	s_cmp_lg_u32 s2, 20
	v_add_u32_e32 v238, s5, v225
	s_cselect_b64 s[2:3], -1, 0
	s_and_b32 s5, s4, 0x7ffffffe
	s_cmp_eq_u32 s5, 6
	s_cselect_b64 s[82:83], -1, 0
	s_sub_i32 s5, s4, 17
	v_add_u32_e32 v239, 0x800, v230
	v_add_u32_e32 v240, 0x1000, v230
	v_add_u32_e32 v241, 0x1800, v230
	s_waitcnt vmcnt(0) lgkmcnt(0)
	s_barrier
	s_mov_b32 s8, 0x0701c030
	s_mov_b32 s34, 0x380e00c0
	s_lshr_b32 s8, s8, s4
	s_lshr_b32 s34, s34, s4
	s_and_b32 s8, s8, 1
	s_and_b32 s34, s34, 1
	s_or_b32 s7, s8, s34
	s_cmp_eq_u32 s7, 0
	s_cbranch_scc1 .Lmy_g0e_std
	v_and_b32_e32 v151, 63, v200
	v_lshrrev_b32_e32 v150, 5, v151
	v_and_b32_e32 v146, 31, v151
	v_lshrrev_b32_e32 v147, 6, v200
	v_lshrrev_b32_e32 v152, 1, v147
	v_and_b32_e32 v148, 1, v147
	v_mul_u32_u24_e32 v147, 0x2200, v147
	v_add_u32_e32 v147, 0x6000, v147
	v_lshlrev_b32_e32 v146, 2, v146
	s_movk_i32 s6, 0x440
	v_mad_u32_u24 v146, v150, s6, v146
	v_add_u32_e32 v146, v146, v147
	v_lshrrev_b32_e32 v150, 4, v151
	v_and_b32_e32 v149, 15, v151
	s_movk_i32 s6, 0x110
	v_mad_u32_u24 v147, v150, s6, v147
	v_lshl_add_u32 v147, v149, 4, v147
	v_lshl_add_u32 v152, v152, 7, s32
	v_add_u32_e32 v152, v152, v150
	s_lshl_b32 s6, s4, 7
	v_lshl_add_u32 v148, v148, 6, s6
	v_lshl_add_u32 v148, v149, 2, v148
	v_lshlrev_b32_e32 v148, 1, v148
	v_mul_u32_u24_e32 v152, 0x1e00, v152
	v_add_u32_e32 v148, v148, v152
	s_mov_b64 s[8:9], s[64:65]
	s_add_i32 s70, s70, s10
	s_mov_b32 s35, 0
	s_cmp_lt_i32 s70, s71
	s_cbranch_scc0 .Lmy_pf_skip
	s_and_b64 vcc, exec, s[40:41]
	s_cbranch_vccnz .Lmy_pf_skip
	s_mul_hi_i32 s6, s70, 0x88888889
	s_add_i32 s6, s6, s70
	s_lshr_b32 s2, s6, 31
	s_ashr_i32 s3, s6, 5
	s_add_i32 s2, s3, s2
	s_mul_i32 s3, s2, 60
	s_ashr_i32 s4, s2, 1
	s_sub_i32 s3, s70, s3
	s_lshl_b32 s5, s4, 2
	v_readlane_b32 s6, v243, 43
	s_add_i32 s5, s5, s6
	s_and_b32 s6, s3, 3
	s_or_b32 s5, s5, s6
	s_xor_b32 s2, s4, s2
	s_bitcmp1_b32 s2, 0
	s_cselect_b32 s2, 15, 0
	s_ashr_i32 s3, s3, 2
	s_add_i32 s4, s2, s3
	s_lshr_b32 s2, s4, 2
	s_and_b32 s3, s4, 3
	s_lshl_b32 s3, s3, 3
	s_mov_b32 s6, 0x1001000a
	s_cmp_eq_u32 s2, 1
	s_cselect_b32 s6, 0x171b0611, s6
	s_cmp_eq_u32 s2, 2
	s_cselect_b32 s6, 0xe1c1d08, s6
	s_cmp_eq_u32 s2, 3
	s_cselect_b32 s6, 0x14090203, s6
	s_cmp_eq_u32 s2, 4
	s_cselect_b32 s6, 0x40f0512, s6
	s_cmp_eq_u32 s2, 5
	s_cselect_b32 s6, 0xc160b0d, s6
	s_cmp_eq_u32 s2, 6
	s_cselect_b32 s6, 0x191a1813, s6
	s_cmp_eq_u32 s2, 7
	s_cselect_b32 s6, 0x1507, s6
	s_lshr_b32 s6, s6, s3
	s_and_b32 s4, s6, 0xff
	s_lshl_b32 s5, s5, 8
	s_lshl_b32 s6, s4, 7
	v_mov_b32_e32 v185, 0
	v_add_u32_e32 v174, s5, v219
	v_ashrrev_i32_e32 v175, 31, v174
	v_lshlrev_b64 v[176:177], 11, v[174:175]
	v_and_b32_e32 v178, 0xfffe7000, v176
	v_mov_b32_e32 v179, v177
	v_lshlrev_b32_e32 v184, 6, v174
	v_lshl_add_u64 v[178:179], s[44:45], 0, v[178:179]
	v_and_b32_e32 v184, 64, v184
	v_lshl_add_u64 v[174:175], v[178:179], 0, v[184:185]
	v_add_u32_e32 v178, s6, v220
	v_ashrrev_i32_e32 v179, 31, v178
	v_lshlrev_b64 v[180:181], 11, v[178:179]
	v_and_b32_e32 v182, 0xffff7000, v180
	v_mov_b32_e32 v183, v181
	v_lshlrev_b32_e32 v184, 6, v178
	v_lshl_add_u64 v[182:183], s[42:43], 0, v[182:183]
	v_and_b32_e32 v184, 64, v184
	v_mov_b32_e32 v139, v1
	v_lshl_add_u64 v[178:179], v[182:183], 0, v[184:185]
	v_lshl_add_u64 v[174:175], v[174:175], 0, v[138:139]
	v_lshl_add_u64 v[178:179], v[178:179], 0, v[138:139]
	v_mov_b32_e32 v0, v221
	s_mov_b64 s[2:3], 0x0
	v_readfirstlane_b32 s7, v0
	v_lshl_add_u64 v[142:143], v[174:175], 0, s[2:3]
	s_mov_b32 m0, s7
	s_nop 0
	global_load_lds_dwordx4 v[142:143], off
	v_add_u32_e32 v0, 0x400, v221
	s_mov_b64 s[2:3], 0x8000
	v_readfirstlane_b32 s7, v0
	v_lshl_add_u64 v[142:143], v[174:175], 0, s[2:3]
	s_mov_b32 m0, s7
	s_nop 0
	global_load_lds_dwordx4 v[142:143], off
	v_add_u32_e32 v0, 0x800, v221
	s_mov_b64 s[2:3], 0x10000
	v_readfirstlane_b32 s7, v0
	v_lshl_add_u64 v[142:143], v[174:175], 0, s[2:3]
	s_mov_b32 m0, s7
	s_nop 0
	global_load_lds_dwordx4 v[142:143], off
	v_add_u32_e32 v0, 0xc00, v221
	s_mov_b64 s[2:3], 0x18000
	v_readfirstlane_b32 s7, v0
	v_lshl_add_u64 v[142:143], v[174:175], 0, s[2:3]
	s_mov_b32 m0, s7
	s_nop 0
	global_load_lds_dwordx4 v[142:143], off
	v_add_u32_e32 v0, 0x4000, v130
	s_mov_b64 s[2:3], 0x0
	v_readfirstlane_b32 s7, v0
	v_lshl_add_u64 v[142:143], v[178:179], 0, s[2:3]
	s_mov_b32 m0, s7
	s_nop 0
	global_load_lds_dwordx4 v[142:143], off
	v_add_u32_e32 v0, 0x4400, v130
	s_mov_b64 s[2:3], 0x8000
	v_readfirstlane_b32 s7, v0
	v_lshl_add_u64 v[142:143], v[178:179], 0, s[2:3]
	s_mov_b32 m0, s7
	s_nop 0
	global_load_lds_dwordx4 v[142:143], off
	s_mov_b32 s35, 0x5aa51234
